# NSA-in and MLA-in GEMM epilogues: the 8 row-stat loads issued together (one wait) instead of 8 serialized round trips
# baseline (speedup 1.0000x reference)
; DI u32x4 pk8(f32x4 a, f32x4 b) { u32x4 o; o.x = pk2(a.x, a.y); o.y = pk2(a.z, a.w); o.z = pk2(b.x, b.y); o.w = pk2(b.z, b.w); return o; }
; DI float sigmoidf_(float x) { return frcp(1.f + fexp2(-x * LOG2E)); }
; #define EPI_SCHED() __builtin_amdgcn_sched_barrier(0)
; template <int STRIDE, int P0, int NP4>
; DI void rstd8(const float* parts, size_t row0, float invK, int fq, float (&rs)[2][4]) {
;     f32x4 v[2][4];
; #pragma unroll
;     for (int ai = 0; ai < 2; ++ai)
; #pragma unroll
;         for (int m = 0; m < 4; ++m) {
;             const float* p = parts + (row0 + ai * 128 + m * 16) * STRIDE + P0;
;             if (NP4 == 1) v[ai][m] = *(const f32x4*)p;
;             else if (fq < NP4) v[ai][m] = *(const f32x4*)(p + 4 * fq);
;             else v[ai][m] = (f32x4){0.f, 0.f, 0.f, 0.f};
;         }
; #pragma unroll
;     for (int ai = 0; ai < 2; ++ai)
; #pragma unroll
;         for (int m = 0; m < 4; ++m) {
;             float t = (v[ai][m].x + v[ai][m].y) + (v[ai][m].z + v[ai][m].w);
;             if (NP4 > 1) { t += __shfl_xor(t, 16); t += __shfl_xor(t, 32); }
;             rs[ai][m] = rsqrtf(t * invK + EPS);
;         }
;     DI void operator()(const AccT& acc, const Unit& u, int wr, int wc, int fr, int fq) const {
;     ...
;                 EPI_SCHED(); const size_t row = row0 + ai * 128 + m * 16;
;                 const size_t b = row >> 11, s = row & 2047;
; #pragma unroll
;                 for (int bj = 0; bj < 2; ++bj) {
;                     const int cc = bj * 128 + wc * 32 + fq * 8;
;                     f32x4 a = acc[ai][bj][m][0] * rs[ai][m], c = acc[ai][bj][m][1] * rs[ai][m];
;                     if (u.pn < 4) *(u32x4*)(q + row * 1024 + u.pn * 256 + cc) = pk8(a, c);
;                     else if (u.pn < 8) { const int g = cc >> 6, d = cc & 63; *(u32x4*)(slab + (size_t)(u.pn - 4) * SLAB_EL + ((b * 4 + g) * 2048 + s) * 64 + d) = pk8(a, c); }
;                     else if (cc < 48) {
; #pragma unroll
;                         for (int e = 0; e < 4; ++e) { a[e] = sigmoidf_(a[e]); c[e] = sigmoidf_(c[e]); }
;                         *(f32x4*)(gates + row * 48 + cc) = a; *(f32x4*)(gates + row * 48 + cc + 4) = c;
.LBB0_1890:
	s_mov_b32 s1, -1
	s_ashr_i32 s3, s2, 31
	v_mbcnt_lo_u32_b32 v0, s1, 0
	v_mbcnt_hi_u32_b32 v130, s1, v0
	s_lshl_b64 s[2:3], s[2:3], 8
	s_add_u32 s4, s2, s65
	v_ashrrev_i32_e32 v0, 4, v130
	s_addc_u32 s5, s3, s84
	v_and_or_b32 v156, v130, 15, s4
	v_lshlrev_b32_e32 v130, 2, v0
	v_mov_b32_e32 v157, s5
	v_ashrrev_i32_e32 v131, 31, v130
	v_cmp_lt_i32_e32 vcc, 3, v0
	v_cmp_gt_i32_e64 s[2:3], 4, v0
	v_lshl_add_u64 v[144:145], v[130:131], 2, s[8:9]
	v_mov_b32_e32 v130, 0
	v_lshlrev_b64 v[158:159], 6, v[156:157]
	v_mov_b32_e32 v134, 0
	v_mov_b32_e32 v160, 0
	v_mov_b32_e32 v161, 0
	v_mov_b32_e32 v135, 0
	v_lshlrev_b64 v[178:179], 6, v[156:157]
	v_lshl_add_u64 v[178:179], v[144:145], 0, v[178:179]
	v_add_co_u32_e32 v180, vcc, 0x2000, v178
	s_nop 1
	v_addc_co_u32_e32 v181, vcc, 0, v179, vcc
	global_load_dwordx4 v[134:137], v[178:179], off
	global_load_dwordx4 v[130:133], v[178:179], off offset:1024
	global_load_dwordx4 v[140:143], v[178:179], off offset:2048
	global_load_dwordx4 v[182:185], v[178:179], off offset:3072
	global_load_dwordx4 v[146:149], v[180:181], off
	global_load_dwordx4 v[186:189], v[180:181], off offset:1024
	global_load_dwordx4 v[152:155], v[180:181], off offset:2048
	global_load_dwordx4 v[190:193], v[180:181], off offset:3072
	s_waitcnt vmcnt(0)
	v_mov_b32_e32 v160, v135
	v_mov_b32_e32 v161, v136
	v_mov_b32_e32 v135, v137
	v_mov_b32_e32 v162, v131
	v_mov_b32_e32 v163, v132
	v_mov_b32_e32 v131, v133
	v_mov_b32_e32 v132, v141
	v_mov_b32_e32 v133, v142
	v_mov_b32_e32 v141, v143
	v_mov_b32_e32 v136, v182
	v_mov_b32_e32 v164, v183
	v_mov_b32_e32 v165, v184
	v_mov_b32_e32 v137, v185
	v_mov_b32_e32 v138, v147
	v_mov_b32_e32 v139, v148
	v_mov_b32_e32 v147, v149
	v_mov_b32_e32 v142, v186
	v_mov_b32_e32 v166, v187
	v_mov_b32_e32 v167, v188
	v_mov_b32_e32 v143, v189
	v_mov_b32_e32 v168, v153
	v_mov_b32_e32 v169, v154
	v_mov_b32_e32 v153, v155
	v_mov_b32_e32 v148, v190
	v_mov_b32_e32 v170, v191
	v_mov_b32_e32 v171, v192
	v_mov_b32_e32 v149, v193
.LBB0_1908:
	v_xor_b32_e32 v144, 16, v207
	v_cmp_lt_i32_e32 vcc, v144, v222
	v_pk_add_f32 v[134:135], v[160:161], v[134:135]
	v_pk_add_f32 v[130:131], v[162:163], v[130:131]
	v_cndmask_b32_e32 v144, v207, v144, vcc
	v_lshlrev_b32_e32 v155, 2, v144
	v_mov_b32_e32 v144, v130
	v_mov_b32_e32 v145, v134
	v_mov_b32_e32 v134, v131
	v_pk_add_f32 v[130:131], v[144:145], v[134:135]
	ds_bpermute_b32 v135, v155, v131
	ds_bpermute_b32 v134, v155, v130
	v_cmp_lt_i32_e32 vcc, v223, v222
	s_cmp_gt_i32 s0, 3
	s_cselect_b64 s[2:3], -1, 0
	v_cndmask_b32_e32 v144, v207, v223, vcc
	v_lshlrev_b32_e32 v159, 2, v144
	s_waitcnt lgkmcnt(0)
	v_pk_add_f32 v[130:131], v[130:131], v[134:135]
	ds_bpermute_b32 v135, v159, v131
	ds_bpermute_b32 v134, v159, v130
	s_cmp_gt_u32 s0, 7
	s_cselect_b64 s[38:39], -1, 0
	s_add_i32 s96, s0, -4
	s_lshr_b64 s[4:5], s[4:5], 9
	s_waitcnt lgkmcnt(0)
	v_pk_add_f32 v[130:131], v[130:131], v[134:135]
	v_mov_b32_e32 v134, 0x358637bd
	v_pk_fma_f32 v[150:151], v[130:131], s[88:89], v[134:135] op_sel_hi:[1,0,0]
	s_lshl_b64 s[34:35], s[96:97], 24
	v_mul_f32_e32 v130, 0x4b800000, v151
	v_cmp_gt_f32_e32 vcc, s42, v151
	v_cmp_gt_f32_e64 s[6:7], s42, v150
	s_and_b32 s49, s5, 0x3fff
	v_cndmask_b32_e32 v130, v151, v130, vcc
	v_rsq_f32_e32 v144, v130
	v_pk_add_f32 v[130:131], v[132:133], v[140:141]
	v_pk_add_f32 v[132:133], v[164:165], v[136:137]
	v_mov_b32_e32 v135, v130
	v_mov_b32_e32 v134, v132
	v_mov_b32_e32 v130, v133
	v_pk_add_f32 v[130:131], v[134:135], v[130:131]
	ds_bpermute_b32 v133, v155, v131
	ds_bpermute_b32 v132, v155, v130
	v_mul_f32_e32 v134, 0x45800000, v144
	v_cndmask_b32_e32 v154, v144, v134, vcc
	v_pk_add_f32 v[136:137], v[170:171], v[148:149]
	s_and_b32 s48, s4, -4
	s_waitcnt lgkmcnt(0)
	v_pk_add_f32 v[140:141], v[130:131], v[132:133]
	v_pk_add_f32 v[130:131], v[138:139], v[146:147]
	v_pk_add_f32 v[132:133], v[166:167], v[142:143]
	v_mov_b32_e32 v135, v130
	v_mov_b32_e32 v134, v132
	v_mov_b32_e32 v130, v133
	v_pk_add_f32 v[130:131], v[134:135], v[130:131]
	v_pk_add_f32 v[134:135], v[168:169], v[152:153]
	v_mov_b32_e32 v138, v136
	v_mov_b32_e32 v139, v134
	v_mov_b32_e32 v134, v137
	v_pk_add_f32 v[134:135], v[138:139], v[134:135]
	ds_bpermute_b32 v133, v155, v131
	ds_bpermute_b32 v132, v155, v130
	ds_bpermute_b32 v143, v155, v135
	ds_bpermute_b32 v142, v155, v134
	ds_bpermute_b32 v145, v159, v141
	ds_bpermute_b32 v144, v159, v140
	s_waitcnt lgkmcnt(0)
	v_pk_add_f32 v[136:137], v[130:131], v[132:133]
	ds_bpermute_b32 v139, v159, v137
	v_pk_add_f32 v[132:133], v[134:135], v[142:143]
	ds_bpermute_b32 v138, v159, v136
	ds_bpermute_b32 v135, v159, v133
	ds_bpermute_b32 v134, v159, v132
	v_lshl_add_u32 v130, v0, 3, s66
	v_mad_u64_u32 v[142:143], s[4:5], v156, 48, 0
	v_mov_b32_e32 v0, v143
	v_mad_u64_u32 v[146:147], s[4:5], v157, 48, v[0:1]
	v_mov_b32_e32 v143, v146
	v_and_b32_e32 v148, 0x1f3c0, v158
	v_pk_mul_f32 v[128:129], v[128:129], v[154:155] op_sel_hi:[1,0]
	v_pk_mul_f32 v[126:127], v[126:127], v[154:155] op_sel_hi:[1,0]
	v_pk_mul_f32 v[124:125], v[124:125], v[154:155] op_sel_hi:[1,0]
	v_pk_mul_f32 v[146:147], v[122:123], v[154:155] op_sel_hi:[1,0]
	s_mov_b64 s[4:5], -1
	s_and_b64 vcc, exec, s[2:3]
	s_cbranch_vccz .LBB0_1916
	s_and_b64 vcc, exec, s[38:39]
	s_cbranch_vccz .LBB0_1913
	v_cmp_gt_i32_e32 vcc, 48, v130
	s_and_saveexec_b64 s[4:5], vcc
	s_cbranch_execz .LBB0_1912
	v_mul_f32_e32 v0, 0xbfb8aa3b, v126
	v_exp_f32_e32 v0, v0
	v_mul_f32_e32 v122, 0xbfb8aa3b, v146
	v_exp_f32_e32 v122, v122
	v_mul_f32_e32 v123, 0xbfb8aa3b, v147
	v_add_f32_e32 v0, 1.0, v0
	v_rcp_f32_e32 v158, v0
	v_mul_f32_e32 v0, 0xbfb8aa3b, v127
	v_exp_f32_e32 v0, v0
	v_exp_f32_e32 v123, v123
	v_add_f32_e32 v122, 1.0, v122
	v_rcp_f32_e32 v162, v122
	v_add_f32_e32 v0, 1.0, v0
	v_mul_f32_e32 v122, 0xbfb8aa3b, v128
	v_rcp_f32_e32 v159, v0
	v_add_f32_e32 v0, 1.0, v123
	v_exp_f32_e32 v122, v122
	v_mul_f32_e32 v123, 0xbfb8aa3b, v124
	v_exp_f32_e32 v123, v123
	v_rcp_f32_e32 v163, v0
	v_add_f32_e32 v0, 1.0, v122
	v_mul_f32_e32 v122, 0xbfb8aa3b, v129
	v_rcp_f32_e32 v160, v0
	v_add_f32_e32 v0, 1.0, v123
	v_exp_f32_e32 v122, v122
	v_mul_f32_e32 v123, 0xbfb8aa3b, v125
	v_exp_f32_e32 v123, v123
	v_rcp_f32_e32 v164, v0
	v_add_f32_e32 v0, 1.0, v122
	v_rcp_f32_e32 v161, v0
	v_add_f32_e32 v0, 1.0, v123
	v_rcp_f32_e32 v165, v0
	v_lshl_add_u64 v[122:123], v[142:143], 2, s[18:19]
	v_ashrrev_i32_e32 v131, 31, v130
	v_lshl_add_u64 v[122:123], v[130:131], 2, v[122:123]
	flat_store_dwordx4 v[122:123], v[158:161]
	flat_store_dwordx4 v[122:123], v[162:165] offset:16

; #define EPI_SCHED() __builtin_amdgcn_sched_barrier(0)
; template <int STRIDE, int P0, int NP4>
; DI void rstd8(const float* parts, size_t row0, float invK, int fq, float (&rs)[2][4]) {
;     f32x4 v[2][4];
; #pragma unroll
;     for (int ai = 0; ai < 2; ++ai)
; #pragma unroll
;         for (int m = 0; m < 4; ++m) {
;             const float* p = parts + (row0 + ai * 128 + m * 16) * STRIDE + P0;
;             if (NP4 == 1) v[ai][m] = *(const f32x4*)p;
;             else if (fq < NP4) v[ai][m] = *(const f32x4*)(p + 4 * fq);
;             else v[ai][m] = (f32x4){0.f, 0.f, 0.f, 0.f};
;         }
; #pragma unroll
;     for (int ai = 0; ai < 2; ++ai)
; #pragma unroll
;         for (int m = 0; m < 4; ++m) {
;             float t = (v[ai][m].x + v[ai][m].y) + (v[ai][m].z + v[ai][m].w);
;             if (NP4 > 1) { t += __shfl_xor(t, 16); t += __shfl_xor(t, 32); }
;             rs[ai][m] = rsqrtf(t * invK + EPS);
;         }
;     DI void operator()(const AccT& acc, const Unit& u, int wr, int wc, int fr, int fq) const {
;         const size_t row0 = (size_t)u.pm * 256 + wr * 64 + fr;
;         float rs[2][4]; rstd8<16, 0, 4>(ss, row0, 1.f / 1024.f, fq, rs);
;         const bool do_rope = (u.pn == 2) && (wc == 0);
; #pragma unroll
;         for (int ai = 0; ai < 2; ++ai) {
;             EPI_SCHED();
;             f32x4 cs[4], sn[4];
;             if (do_rope) {
; #pragma unroll
;                 for (int m = 0; m < 4; ++m) { const int s = (int)((row0 + ai * 128 + m * 16) & 2047); cs[m] = *(const f32x4*)(rope + s * 16 + 4 * fq); sn[m] = *(const f32x4*)(rope + 32768 + s * 16 + 4 * fq); }
.LBB0_2501:
	s_mov_b32 s1, -1
	v_mov_b32_e32 v98, 0
	v_mbcnt_lo_u32_b32 v0, s1, 0
	v_mbcnt_hi_u32_b32 v195, s1, v0
	s_ashr_i32 s1, s0, 31
	s_lshl_b64 s[0:1], s[0:1], 8
	v_ashrrev_i32_e32 v196, 4, v195
	s_add_u32 s0, s0, s64
	v_lshlrev_b32_e32 v164, 2, v196
	s_addc_u32 s1, s1, s69
	v_ashrrev_i32_e32 v165, 31, v164
	v_and_or_b32 v162, v195, 15, s0
	v_mov_b32_e32 v163, s1
	v_cmp_gt_i32_e64 s[0:1], 4, v196
	v_lshl_add_u64 v[156:157], v[164:165], 2, s[16:17]
	v_mov_b32_e32 v102, 0
	v_mov_b32_e32 v166, 0
	v_mov_b32_e32 v167, 0
	v_mov_b32_e32 v103, 0
	v_lshlrev_b64 v[168:169], 6, v[162:163]
	v_lshl_add_u64 v[168:169], v[156:157], 0, v[168:169]
	v_add_co_u32_e32 v170, vcc, 0x2000, v168
	s_nop 1
	v_addc_co_u32_e32 v171, vcc, 0, v169, vcc
	global_load_dwordx4 v[102:105], v[168:169], off
	global_load_dwordx4 v[98:101], v[168:169], off offset:1024
	global_load_dwordx4 v[126:129], v[168:169], off offset:2048
	global_load_dwordx4 v[122:125], v[168:169], off offset:3072
	global_load_dwordx4 v[142:145], v[170:171], off
	global_load_dwordx4 v[138:141], v[170:171], off offset:1024
	global_load_dwordx4 v[158:161], v[170:171], off offset:2048
	global_load_dwordx4 v[154:157], v[170:171], off offset:3072
	s_waitcnt vmcnt(0)
	v_mov_b32_e32 v166, v103
	v_mov_b32_e32 v167, v104
	v_mov_b32_e32 v103, v105
	v_mov_b32_e32 v104, v99
	v_mov_b32_e32 v105, v100
	v_mov_b32_e32 v99, v101
	v_mov_b32_e32 v100, v127
	v_mov_b32_e32 v101, v128
	v_mov_b32_e32 v127, v129
	v_mov_b32_e32 v128, v123
	v_mov_b32_e32 v129, v124
	v_mov_b32_e32 v123, v125
	v_mov_b32_e32 v124, v143
	v_mov_b32_e32 v125, v144
	v_mov_b32_e32 v143, v145
	v_mov_b32_e32 v144, v139
	v_mov_b32_e32 v145, v140
	v_mov_b32_e32 v139, v141
	v_mov_b32_e32 v140, v159
	v_mov_b32_e32 v141, v160
	v_mov_b32_e32 v159, v161
	v_mov_b32_e32 v160, v155
	v_mov_b32_e32 v161, v156
	v_mov_b32_e32 v155, v157
.LBB0_2517:
	v_pk_add_f32 v[102:103], v[166:167], v[102:103]
	v_pk_add_f32 v[98:99], v[104:105], v[98:99]
	v_xor_b32_e32 v0, 16, v207
	v_mov_b32_e32 v104, v98
	v_mov_b32_e32 v105, v102
	v_mov_b32_e32 v102, v99
	v_cmp_lt_i32_e32 vcc, v0, v222
	v_pk_add_f32 v[98:99], v[104:105], v[102:103]
	v_pk_add_f32 v[100:101], v[100:101], v[126:127]
	v_pk_add_f32 v[104:105], v[128:129], v[122:123]
	v_cndmask_b32_e32 v0, v207, v0, vcc
	v_mov_b32_e32 v122, v104
	v_mov_b32_e32 v123, v100
	v_mov_b32_e32 v100, v105
	v_lshlrev_b32_e32 v192, 2, v0
	v_pk_add_f32 v[100:101], v[122:123], v[100:101]
	ds_bpermute_b32 v103, v192, v99
	ds_bpermute_b32 v102, v192, v98
	ds_bpermute_b32 v105, v192, v101
	ds_bpermute_b32 v104, v192, v100
	v_cmp_lt_i32_e32 vcc, v223, v222
	s_cmp_lg_u32 s38, 2
	s_waitcnt lgkmcnt(0)
	v_pk_add_f32 v[170:171], v[98:99], v[102:103]
	v_pk_add_f32 v[98:99], v[124:125], v[142:143]
	v_pk_add_f32 v[180:181], v[100:101], v[104:105]
	v_pk_add_f32 v[100:101], v[144:145], v[138:139]
	v_mov_b32_e32 v103, v98
	v_mov_b32_e32 v102, v100
	v_mov_b32_e32 v98, v101
	v_pk_add_f32 v[98:99], v[102:103], v[98:99]
	v_pk_add_f32 v[102:103], v[140:141], v[158:159]
	v_pk_add_f32 v[104:105], v[160:161], v[154:155]
	v_mov_b32_e32 v123, v102
	v_mov_b32_e32 v122, v104
	v_mov_b32_e32 v102, v105
	v_pk_add_f32 v[102:103], v[122:123], v[102:103]
	ds_bpermute_b32 v101, v192, v99
	ds_bpermute_b32 v100, v192, v98
	ds_bpermute_b32 v105, v192, v103
	ds_bpermute_b32 v104, v192, v102
	v_cndmask_b32_e32 v0, v207, v223, vcc
	v_lshlrev_b32_e32 v193, 2, v0
	s_waitcnt lgkmcnt(0)
	v_pk_add_f32 v[172:173], v[98:99], v[100:101]
	ds_bpermute_b32 v185, v193, v171
	v_pk_add_f32 v[166:167], v[102:103], v[104:105]
	ds_bpermute_b32 v184, v193, v170
	ds_bpermute_b32 v183, v193, v181
	ds_bpermute_b32 v182, v193, v180
	ds_bpermute_b32 v175, v193, v173
	ds_bpermute_b32 v174, v193, v172
	ds_bpermute_b32 v169, v193, v167
	ds_bpermute_b32 v168, v193, v166
	s_cselect_b64 s[2:3], -1, 0
	s_cmp_eq_u32 s38, 2
	s_cselect_b64 s[0:1], -1, 0
	v_lshlrev_b32_e32 v194, 4, v162
	s_and_b64 s[0:1], s[26:27], s[0:1]
	v_mov_b32_e32 v154, 0
	v_cndmask_b32_e64 v0, 0, 1, s[0:1]
	v_lshlrev_b64 v[98:99], 2, v[164:165]
	v_cmp_ne_u32_e64 s[6:7], 1, v0
	s_andn2_b64 vcc, exec, s[0:1]
	v_lshl_add_u64 v[178:179], s[12:13], 0, v[98:99]
	v_lshl_add_u64 v[176:177], s[28:29], 0, v[98:99]
	v_mov_b32_e32 v155, v154
	v_mov_b32_e32 v156, v154
	v_mov_b32_e32 v157, v154
	v_mov_b32_e32 v142, v154
	v_mov_b32_e32 v143, v154
	v_mov_b32_e32 v144, v154
	v_mov_b32_e32 v145, v154
	v_mov_b32_e32 v126, v154
	v_mov_b32_e32 v127, v154
	v_mov_b32_e32 v128, v154
	v_mov_b32_e32 v129, v154
	v_mov_b32_e32 v98, v154
	v_mov_b32_e32 v99, v154
	v_mov_b32_e32 v100, v154
	v_mov_b32_e32 v101, v154
	s_cbranch_vccnz .LBB0_2519
	v_and_b32_e32 v0, 0x7cf0, v194
	v_lshlrev_b32_e32 v0, 2, v0
	v_lshl_add_u64 v[98:99], v[178:179], 0, v[0:1]
	v_lshl_add_u64 v[102:103], v[176:177], 0, v[0:1]
	flat_load_dwordx4 v[154:157], v[98:99]
	flat_load_dwordx4 v[142:145], v[98:99] offset:1024
	flat_load_dwordx4 v[158:161], v[102:103]
	flat_load_dwordx4 v[138:141], v[102:103] offset:1024
	flat_load_dwordx4 v[126:129], v[98:99] offset:2048
	s_nop 0
	flat_load_dwordx4 v[98:101], v[98:99] offset:3072
	s_nop 0
	flat_load_dwordx4 v[122:125], v[102:103] offset:2048
	s_nop 0
	flat_load_dwordx4 v[102:105], v[102:103] offset:3072
